# MLA prompt loop micro-trims: shorter max chain, merged causal-skip test, branch-free masked LDS stores
# speedup vs baseline: 1.0021x; 1.0021x over previous
.Lst_top:
	s_add_i32 s93, s69, 0
	s_cmp_gt_i32 s93, s50
	s_cbranch_scc1 .Lst_nosm0
	ds_read_b128 v[220:223], v194
	ds_read_b128 v[224:227], v194 offset:32
	ds_read_b128 v[228:231], v194 offset:64
	ds_read_b128 v[232:235], v194 offset:96
	ds_read_b128 v[126:129], v194 offset:256
	ds_read_b128 v[130:133], v194 offset:288
	ds_read_b128 v[134:137], v194 offset:10752
	ds_read_b128 v[212:215], v194 offset:10784
	ds_read_b128 v[154:157], v194 offset:10816
	ds_read_b128 v[158:161], v194 offset:10848
	ds_read_b128 v[204:207], v194 offset:11008
	ds_read_b128 v[186:189], v194 offset:11040
	s_waitcnt lgkmcnt(11)
	v_mfma_f32_32x32x16_bf16 v[48:63], v[220:223], v[64:67], v[236:251]
	s_waitcnt lgkmcnt(10)
	v_mfma_f32_32x32x16_bf16 v[48:63], v[224:227], v[68:71], v[48:63]
	s_waitcnt lgkmcnt(9)
	v_mfma_f32_32x32x16_bf16 v[48:63], v[228:231], v[72:75], v[48:63]
	s_waitcnt lgkmcnt(8)
	v_mfma_f32_32x32x16_bf16 v[48:63], v[232:235], v[76:79], v[48:63]
	s_waitcnt lgkmcnt(7)
	v_mfma_f32_32x32x16_bf16 v[48:63], v[126:129], v[80:83], v[48:63]
	s_waitcnt lgkmcnt(6)
	v_mfma_f32_32x32x16_bf16 v[48:63], v[130:133], v[84:87], v[48:63]
	s_waitcnt lgkmcnt(5)
	v_mfma_f32_32x32x16_bf16 v[32:47], v[134:137], v[64:67], v[236:251]
	s_waitcnt lgkmcnt(4)
	v_mfma_f32_32x32x16_bf16 v[32:47], v[212:215], v[68:71], v[32:47]
	s_waitcnt lgkmcnt(3)
	v_mfma_f32_32x32x16_bf16 v[32:47], v[154:157], v[72:75], v[32:47]
	s_waitcnt lgkmcnt(2)
	v_mfma_f32_32x32x16_bf16 v[32:47], v[158:161], v[76:79], v[32:47]
	s_waitcnt lgkmcnt(1)
	v_mfma_f32_32x32x16_bf16 v[32:47], v[204:207], v[80:83], v[32:47]
	s_waitcnt lgkmcnt(0)
	v_mfma_f32_32x32x16_bf16 v[32:47], v[186:189], v[84:87], v[32:47]
	v_max3_f32 v153, v48, v49, v50
	v_max3_f32 v153, v153, v51, v52
	v_max3_f32 v153, v153, v53, v54
	v_max3_f32 v153, v153, v55, v56
	v_max3_f32 v153, v153, v57, v58
	v_max3_f32 v153, v153, v59, v60
	v_max3_f32 v153, v153, v61, v62
	v_max_f32_e32 v153, v153, v63
	s_nop 3
	v_max3_f32 v153, v153, v32, v33
	v_max3_f32 v153, v153, v34, v35
	v_max3_f32 v153, v153, v36, v37
	v_max3_f32 v153, v153, v38, v39
	v_max3_f32 v153, v153, v40, v41
	v_max3_f32 v153, v153, v42, v43
	v_max3_f32 v153, v153, v44, v45
	v_max3_f32 v153, v153, v46, v47
	s_cmp_eq_u32 s93, 0
	s_cbranch_scc1 .Lst_first
	v_cmp_lt_f32_e32 vcc, 0x41000000, v153
	s_cbranch_vccz .Lst_norescale_0
	v_mov_b32_e32 v154, v153
	s_nop 1
	v_permlane32_swap_b32_e32 v153, v154
	v_max_f32_e32 v153, v153, v154
	v_max_f32_e32 v154, 0, v153
	v_exp_f32_e64 v152, -v154
	v_sub_f32_e32 v236, v236, v154
	v_sub_f32_e32 v237, v237, v154
	v_sub_f32_e32 v238, v238, v154
	v_sub_f32_e32 v239, v239, v154
	v_sub_f32_e32 v240, v240, v154
	v_sub_f32_e32 v241, v241, v154
	v_sub_f32_e32 v242, v242, v154
	v_sub_f32_e32 v243, v243, v154
	v_sub_f32_e32 v244, v244, v154
	v_sub_f32_e32 v245, v245, v154
	v_sub_f32_e32 v246, v246, v154
	v_sub_f32_e32 v247, v247, v154
	v_sub_f32_e32 v248, v248, v154
	v_sub_f32_e32 v249, v249, v154
	v_sub_f32_e32 v250, v250, v154
	v_sub_f32_e32 v251, v251, v154
	v_pk_mul_f32 v[30:31], v[30:31], v[152:153] op_sel_hi:[1,0]
	v_pk_mul_f32 v[28:29], v[28:29], v[152:153] op_sel_hi:[1,0]
	v_pk_mul_f32 v[26:27], v[26:27], v[152:153] op_sel_hi:[1,0]
	v_pk_mul_f32 v[24:25], v[24:25], v[152:153] op_sel_hi:[1,0]
	v_pk_mul_f32 v[22:23], v[22:23], v[152:153] op_sel_hi:[1,0]
	v_pk_mul_f32 v[20:21], v[20:21], v[152:153] op_sel_hi:[1,0]
	v_pk_mul_f32 v[18:19], v[18:19], v[152:153] op_sel_hi:[1,0]
	v_pk_mul_f32 v[16:17], v[16:17], v[152:153] op_sel_hi:[1,0]
	v_pk_mul_f32 v[14:15], v[14:15], v[152:153] op_sel_hi:[1,0]
	v_pk_mul_f32 v[12:13], v[12:13], v[152:153] op_sel_hi:[1,0]
	v_pk_mul_f32 v[10:11], v[10:11], v[152:153] op_sel_hi:[1,0]
	v_pk_mul_f32 v[8:9], v[8:9], v[152:153] op_sel_hi:[1,0]
	v_pk_mul_f32 v[6:7], v[6:7], v[152:153] op_sel_hi:[1,0]
	v_pk_mul_f32 v[4:5], v[4:5], v[152:153] op_sel_hi:[1,0]
	v_pk_mul_f32 v[2:3], v[2:3], v[152:153] op_sel_hi:[1,0]
	v_pk_mul_f32 v[0:1], v[0:1], v[152:153] op_sel_hi:[1,0]
	v_mul_f32_e32 v151, v151, v152

.Lst_nosm0:
	s_cmp_ge_u32 s93, s51
	s_cbranch_scc1 .Lst_a0_nost
	s_waitcnt vmcnt(0)
	s_and_saveexec_b64 s[66:67], s[8:9]
	ds_write_b128 v203, v[100:103] offset:21504
	s_mov_b64 exec, s[10:11]
	ds_write_b128 v252, v[104:107] offset:21504
	s_mov_b64 exec, s[12:13]
	ds_write_b128 v253, v[108:111] offset:21504
	s_mov_b64 exec, s[66:67]
.Lst_a0_nost:
	s_cmp_ge_u32 s93, s60
	s_cbranch_scc1 .Lst_a0_nold
	global_load_dwordx4 v[100:103], v190, s[30:31]
	v_add_u32_e32 v190, v197, v190
	global_load_dwordx4 v[104:107], v191, s[30:31]
	v_add_u32_e32 v191, v208, v191
	s_and_saveexec_b64 s[66:67], s[12:13]
	global_load_dwordx4 v[108:111], v196, s[30:31]
	v_add_u32_e32 v196, v209, v196
	s_mov_b64 exec, s[66:67]
.Lst_a0_nold:
.Lst_bar2_0:
	s_waitcnt lgkmcnt(0)
	s_barrier
	s_add_i32 s93, s69, 1
	s_cmp_ge_u32 s93, s47
	s_cbranch_scc1 .Lst_exit
	s_cmp_gt_i32 s93, s50
	s_cbranch_scc1 .Lst_nosm1
	ds_read_b128 v[220:223], v194 offset:21504
	ds_read_b128 v[224:227], v194 offset:21536
	ds_read_b128 v[228:231], v194 offset:21568
	ds_read_b128 v[232:235], v194 offset:21600
	ds_read_b128 v[126:129], v194 offset:21760
	ds_read_b128 v[130:133], v194 offset:21792
	ds_read_b128 v[134:137], v194 offset:32256
	ds_read_b128 v[212:215], v194 offset:32288
	ds_read_b128 v[154:157], v194 offset:32320
	ds_read_b128 v[158:161], v194 offset:32352
	ds_read_b128 v[204:207], v194 offset:32512
	ds_read_b128 v[186:189], v194 offset:32544
	s_waitcnt lgkmcnt(11)
	v_mfma_f32_32x32x16_bf16 v[48:63], v[220:223], v[64:67], v[236:251]
	s_waitcnt lgkmcnt(10)
	v_mfma_f32_32x32x16_bf16 v[48:63], v[224:227], v[68:71], v[48:63]
	s_waitcnt lgkmcnt(9)
	v_mfma_f32_32x32x16_bf16 v[48:63], v[228:231], v[72:75], v[48:63]
	s_waitcnt lgkmcnt(8)
	v_mfma_f32_32x32x16_bf16 v[48:63], v[232:235], v[76:79], v[48:63]
	s_waitcnt lgkmcnt(7)
	v_mfma_f32_32x32x16_bf16 v[48:63], v[126:129], v[80:83], v[48:63]
	s_waitcnt lgkmcnt(6)
	v_mfma_f32_32x32x16_bf16 v[48:63], v[130:133], v[84:87], v[48:63]
	s_waitcnt lgkmcnt(5)
	v_mfma_f32_32x32x16_bf16 v[32:47], v[134:137], v[64:67], v[236:251]
	s_waitcnt lgkmcnt(4)
	v_mfma_f32_32x32x16_bf16 v[32:47], v[212:215], v[68:71], v[32:47]
	s_waitcnt lgkmcnt(3)
	v_mfma_f32_32x32x16_bf16 v[32:47], v[154:157], v[72:75], v[32:47]
	s_waitcnt lgkmcnt(2)
	v_mfma_f32_32x32x16_bf16 v[32:47], v[158:161], v[76:79], v[32:47]
	s_waitcnt lgkmcnt(1)
	v_mfma_f32_32x32x16_bf16 v[32:47], v[204:207], v[80:83], v[32:47]
	s_waitcnt lgkmcnt(0)
	v_mfma_f32_32x32x16_bf16 v[32:47], v[186:189], v[84:87], v[32:47]
	v_max3_f32 v153, v48, v49, v50
	v_max3_f32 v153, v153, v51, v52
	v_max3_f32 v153, v153, v53, v54
	v_max3_f32 v153, v153, v55, v56
	v_max3_f32 v153, v153, v57, v58
	v_max3_f32 v153, v153, v59, v60
	v_max3_f32 v153, v153, v61, v62
	v_max_f32_e32 v153, v153, v63
	s_nop 3
	v_max3_f32 v153, v153, v32, v33
	v_max3_f32 v153, v153, v34, v35
	v_max3_f32 v153, v153, v36, v37
	v_max3_f32 v153, v153, v38, v39
	v_max3_f32 v153, v153, v40, v41
	v_max3_f32 v153, v153, v42, v43
	v_max3_f32 v153, v153, v44, v45
	v_max3_f32 v153, v153, v46, v47
	v_cmp_lt_f32_e32 vcc, 0x41000000, v153
	s_cbranch_vccz .Lst_norescale_1
	v_mov_b32_e32 v154, v153
	s_nop 1
	v_permlane32_swap_b32_e32 v153, v154
	v_max_f32_e32 v153, v153, v154
	v_max_f32_e32 v154, 0, v153
	v_exp_f32_e64 v152, -v154
	v_sub_f32_e32 v236, v236, v154
	v_sub_f32_e32 v237, v237, v154
	v_sub_f32_e32 v238, v238, v154
	v_sub_f32_e32 v239, v239, v154
	v_sub_f32_e32 v240, v240, v154
	v_sub_f32_e32 v241, v241, v154
	v_sub_f32_e32 v242, v242, v154
	v_sub_f32_e32 v243, v243, v154
	v_sub_f32_e32 v244, v244, v154
	v_sub_f32_e32 v245, v245, v154
	v_sub_f32_e32 v246, v246, v154
	v_sub_f32_e32 v247, v247, v154
	v_sub_f32_e32 v248, v248, v154
	v_sub_f32_e32 v249, v249, v154
	v_sub_f32_e32 v250, v250, v154
	v_sub_f32_e32 v251, v251, v154
	v_pk_mul_f32 v[30:31], v[30:31], v[152:153] op_sel_hi:[1,0]
	v_pk_mul_f32 v[28:29], v[28:29], v[152:153] op_sel_hi:[1,0]
	v_pk_mul_f32 v[26:27], v[26:27], v[152:153] op_sel_hi:[1,0]
	v_pk_mul_f32 v[24:25], v[24:25], v[152:153] op_sel_hi:[1,0]
	v_pk_mul_f32 v[22:23], v[22:23], v[152:153] op_sel_hi:[1,0]
	v_pk_mul_f32 v[20:21], v[20:21], v[152:153] op_sel_hi:[1,0]
	v_pk_mul_f32 v[18:19], v[18:19], v[152:153] op_sel_hi:[1,0]
	v_pk_mul_f32 v[16:17], v[16:17], v[152:153] op_sel_hi:[1,0]
	v_pk_mul_f32 v[14:15], v[14:15], v[152:153] op_sel_hi:[1,0]
	v_pk_mul_f32 v[12:13], v[12:13], v[152:153] op_sel_hi:[1,0]
	v_pk_mul_f32 v[10:11], v[10:11], v[152:153] op_sel_hi:[1,0]
	v_pk_mul_f32 v[8:9], v[8:9], v[152:153] op_sel_hi:[1,0]
	v_pk_mul_f32 v[6:7], v[6:7], v[152:153] op_sel_hi:[1,0]
	v_pk_mul_f32 v[4:5], v[4:5], v[152:153] op_sel_hi:[1,0]
	v_pk_mul_f32 v[2:3], v[2:3], v[152:153] op_sel_hi:[1,0]
	v_pk_mul_f32 v[0:1], v[0:1], v[152:153] op_sel_hi:[1,0]
	v_mul_f32_e32 v151, v151, v152

.Lst_nosm1:
	s_cmp_ge_u32 s93, s51
	s_cbranch_scc1 .Lst_a1_nost
	s_waitcnt vmcnt(0)
	s_and_saveexec_b64 s[66:67], s[8:9]
	ds_write_b128 v203, v[112:115]
	s_mov_b64 exec, s[10:11]
	ds_write_b128 v252, v[116:119]
	s_mov_b64 exec, s[12:13]
	ds_write_b128 v253, v[120:123]
	s_mov_b64 exec, s[66:67]
.Lst_a1_nost:
	s_cmp_ge_u32 s93, s60
	s_cbranch_scc1 .Lst_a1_nold
	global_load_dwordx4 v[112:115], v190, s[30:31]
	v_add_u32_e32 v190, v197, v190
	global_load_dwordx4 v[116:119], v191, s[30:31]
	v_add_u32_e32 v191, v208, v191
	s_and_saveexec_b64 s[66:67], s[12:13]
	global_load_dwordx4 v[120:123], v196, s[30:31]
	v_add_u32_e32 v196, v209, v196
	s_mov_b64 exec, s[66:67]
.Lst_a1_nold:
.Lst_bar2_1:
	s_waitcnt lgkmcnt(0)
	s_barrier
	s_add_i32 s93, s69, 2
	s_cmp_ge_u32 s93, s47
	s_cbranch_scc1 .Lst_exit
	s_cmp_gt_i32 s93, s50
	s_cbranch_scc1 .Lst_nosm2
	ds_read_b128 v[220:223], v194
	ds_read_b128 v[224:227], v194 offset:32
	ds_read_b128 v[228:231], v194 offset:64
	ds_read_b128 v[232:235], v194 offset:96
	ds_read_b128 v[126:129], v194 offset:256
	ds_read_b128 v[130:133], v194 offset:288
	ds_read_b128 v[134:137], v194 offset:10752
	ds_read_b128 v[212:215], v194 offset:10784
	ds_read_b128 v[154:157], v194 offset:10816
	ds_read_b128 v[158:161], v194 offset:10848
	ds_read_b128 v[204:207], v194 offset:11008
	ds_read_b128 v[186:189], v194 offset:11040
	s_waitcnt lgkmcnt(11)
	v_mfma_f32_32x32x16_bf16 v[48:63], v[220:223], v[64:67], v[236:251]
	s_waitcnt lgkmcnt(10)
	v_mfma_f32_32x32x16_bf16 v[48:63], v[224:227], v[68:71], v[48:63]
	s_waitcnt lgkmcnt(9)
	v_mfma_f32_32x32x16_bf16 v[48:63], v[228:231], v[72:75], v[48:63]
	s_waitcnt lgkmcnt(8)
	v_mfma_f32_32x32x16_bf16 v[48:63], v[232:235], v[76:79], v[48:63]
	s_waitcnt lgkmcnt(7)
	v_mfma_f32_32x32x16_bf16 v[48:63], v[126:129], v[80:83], v[48:63]
	s_waitcnt lgkmcnt(6)
	v_mfma_f32_32x32x16_bf16 v[48:63], v[130:133], v[84:87], v[48:63]
	s_waitcnt lgkmcnt(5)
	v_mfma_f32_32x32x16_bf16 v[32:47], v[134:137], v[64:67], v[236:251]
	s_waitcnt lgkmcnt(4)
	v_mfma_f32_32x32x16_bf16 v[32:47], v[212:215], v[68:71], v[32:47]
	s_waitcnt lgkmcnt(3)
	v_mfma_f32_32x32x16_bf16 v[32:47], v[154:157], v[72:75], v[32:47]
	s_waitcnt lgkmcnt(2)
	v_mfma_f32_32x32x16_bf16 v[32:47], v[158:161], v[76:79], v[32:47]
	s_waitcnt lgkmcnt(1)
	v_mfma_f32_32x32x16_bf16 v[32:47], v[204:207], v[80:83], v[32:47]
	s_waitcnt lgkmcnt(0)
	v_mfma_f32_32x32x16_bf16 v[32:47], v[186:189], v[84:87], v[32:47]
	v_max3_f32 v153, v48, v49, v50
	v_max3_f32 v153, v153, v51, v52
	v_max3_f32 v153, v153, v53, v54
	v_max3_f32 v153, v153, v55, v56
	v_max3_f32 v153, v153, v57, v58
	v_max3_f32 v153, v153, v59, v60
	v_max3_f32 v153, v153, v61, v62
	v_max_f32_e32 v153, v153, v63
	s_nop 3
	v_max3_f32 v153, v153, v32, v33
	v_max3_f32 v153, v153, v34, v35
	v_max3_f32 v153, v153, v36, v37
	v_max3_f32 v153, v153, v38, v39
	v_max3_f32 v153, v153, v40, v41
	v_max3_f32 v153, v153, v42, v43
	v_max3_f32 v153, v153, v44, v45
	v_max3_f32 v153, v153, v46, v47
	v_cmp_lt_f32_e32 vcc, 0x41000000, v153
	s_cbranch_vccz .Lst_norescale_2
	v_mov_b32_e32 v154, v153
	s_nop 1
	v_permlane32_swap_b32_e32 v153, v154
	v_max_f32_e32 v153, v153, v154
	v_max_f32_e32 v154, 0, v153
	v_exp_f32_e64 v152, -v154
	v_sub_f32_e32 v236, v236, v154
	v_sub_f32_e32 v237, v237, v154
	v_sub_f32_e32 v238, v238, v154
	v_sub_f32_e32 v239, v239, v154
	v_sub_f32_e32 v240, v240, v154
	v_sub_f32_e32 v241, v241, v154
	v_sub_f32_e32 v242, v242, v154
	v_sub_f32_e32 v243, v243, v154
	v_sub_f32_e32 v244, v244, v154
	v_sub_f32_e32 v245, v245, v154
	v_sub_f32_e32 v246, v246, v154
	v_sub_f32_e32 v247, v247, v154
	v_sub_f32_e32 v248, v248, v154
	v_sub_f32_e32 v249, v249, v154
	v_sub_f32_e32 v250, v250, v154
	v_sub_f32_e32 v251, v251, v154
	v_pk_mul_f32 v[30:31], v[30:31], v[152:153] op_sel_hi:[1,0]
	v_pk_mul_f32 v[28:29], v[28:29], v[152:153] op_sel_hi:[1,0]
	v_pk_mul_f32 v[26:27], v[26:27], v[152:153] op_sel_hi:[1,0]
	v_pk_mul_f32 v[24:25], v[24:25], v[152:153] op_sel_hi:[1,0]
	v_pk_mul_f32 v[22:23], v[22:23], v[152:153] op_sel_hi:[1,0]
	v_pk_mul_f32 v[20:21], v[20:21], v[152:153] op_sel_hi:[1,0]
	v_pk_mul_f32 v[18:19], v[18:19], v[152:153] op_sel_hi:[1,0]
	v_pk_mul_f32 v[16:17], v[16:17], v[152:153] op_sel_hi:[1,0]
	v_pk_mul_f32 v[14:15], v[14:15], v[152:153] op_sel_hi:[1,0]
	v_pk_mul_f32 v[12:13], v[12:13], v[152:153] op_sel_hi:[1,0]
	v_pk_mul_f32 v[10:11], v[10:11], v[152:153] op_sel_hi:[1,0]
	v_pk_mul_f32 v[8:9], v[8:9], v[152:153] op_sel_hi:[1,0]
	v_pk_mul_f32 v[6:7], v[6:7], v[152:153] op_sel_hi:[1,0]
	v_pk_mul_f32 v[4:5], v[4:5], v[152:153] op_sel_hi:[1,0]
	v_pk_mul_f32 v[2:3], v[2:3], v[152:153] op_sel_hi:[1,0]
	v_pk_mul_f32 v[0:1], v[0:1], v[152:153] op_sel_hi:[1,0]
	v_mul_f32_e32 v151, v151, v152

.Lst_nosm2:
	s_cmp_ge_u32 s93, s51
	s_cbranch_scc1 .Lst_a2_nost
	s_waitcnt vmcnt(0)
	s_and_saveexec_b64 s[66:67], s[8:9]
	ds_write_b128 v203, v[88:91] offset:21504
	s_mov_b64 exec, s[10:11]
	ds_write_b128 v252, v[92:95] offset:21504
	s_mov_b64 exec, s[12:13]
	ds_write_b128 v253, v[96:99] offset:21504
	s_mov_b64 exec, s[66:67]
.Lst_a2_nost:
	s_cmp_ge_u32 s93, s60
	s_cbranch_scc1 .Lst_a2_nold
	global_load_dwordx4 v[88:91], v190, s[30:31]
	v_add_u32_e32 v190, v197, v190
	global_load_dwordx4 v[92:95], v191, s[30:31]
	v_add_u32_e32 v191, v208, v191
	s_and_saveexec_b64 s[66:67], s[12:13]
	global_load_dwordx4 v[96:99], v196, s[30:31]
	v_add_u32_e32 v196, v209, v196
	s_mov_b64 exec, s[66:67]
.Lst_a2_nold:
.Lst_bar2_2:
	s_waitcnt lgkmcnt(0)
	s_barrier
	s_add_i32 s93, s69, 3
	s_cmp_ge_u32 s93, s47
	s_cbranch_scc1 .Lst_exit
	s_cmp_gt_i32 s93, s50
	s_cbranch_scc1 .Lst_nosm3
	ds_read_b128 v[220:223], v194 offset:21504
	ds_read_b128 v[224:227], v194 offset:21536
	ds_read_b128 v[228:231], v194 offset:21568
	ds_read_b128 v[232:235], v194 offset:21600
	ds_read_b128 v[126:129], v194 offset:21760
	ds_read_b128 v[130:133], v194 offset:21792
	ds_read_b128 v[134:137], v194 offset:32256
	ds_read_b128 v[212:215], v194 offset:32288
	ds_read_b128 v[154:157], v194 offset:32320
	ds_read_b128 v[158:161], v194 offset:32352
	ds_read_b128 v[204:207], v194 offset:32512
	ds_read_b128 v[186:189], v194 offset:32544
	s_waitcnt lgkmcnt(11)
	v_mfma_f32_32x32x16_bf16 v[48:63], v[220:223], v[64:67], v[236:251]
	s_waitcnt lgkmcnt(10)
	v_mfma_f32_32x32x16_bf16 v[48:63], v[224:227], v[68:71], v[48:63]
	s_waitcnt lgkmcnt(9)
	v_mfma_f32_32x32x16_bf16 v[48:63], v[228:231], v[72:75], v[48:63]
	s_waitcnt lgkmcnt(8)
	v_mfma_f32_32x32x16_bf16 v[48:63], v[232:235], v[76:79], v[48:63]
	s_waitcnt lgkmcnt(7)
	v_mfma_f32_32x32x16_bf16 v[48:63], v[126:129], v[80:83], v[48:63]
	s_waitcnt lgkmcnt(6)
	v_mfma_f32_32x32x16_bf16 v[48:63], v[130:133], v[84:87], v[48:63]
	s_waitcnt lgkmcnt(5)
	v_mfma_f32_32x32x16_bf16 v[32:47], v[134:137], v[64:67], v[236:251]
	s_waitcnt lgkmcnt(4)
	v_mfma_f32_32x32x16_bf16 v[32:47], v[212:215], v[68:71], v[32:47]
	s_waitcnt lgkmcnt(3)
	v_mfma_f32_32x32x16_bf16 v[32:47], v[154:157], v[72:75], v[32:47]
	s_waitcnt lgkmcnt(2)
	v_mfma_f32_32x32x16_bf16 v[32:47], v[158:161], v[76:79], v[32:47]
	s_waitcnt lgkmcnt(1)
	v_mfma_f32_32x32x16_bf16 v[32:47], v[204:207], v[80:83], v[32:47]
	s_waitcnt lgkmcnt(0)
	v_mfma_f32_32x32x16_bf16 v[32:47], v[186:189], v[84:87], v[32:47]
	v_max3_f32 v153, v48, v49, v50
	v_max3_f32 v153, v153, v51, v52
	v_max3_f32 v153, v153, v53, v54
	v_max3_f32 v153, v153, v55, v56
	v_max3_f32 v153, v153, v57, v58
	v_max3_f32 v153, v153, v59, v60
	v_max3_f32 v153, v153, v61, v62
	v_max_f32_e32 v153, v153, v63
	s_nop 3
	v_max3_f32 v153, v153, v32, v33
	v_max3_f32 v153, v153, v34, v35
	v_max3_f32 v153, v153, v36, v37
	v_max3_f32 v153, v153, v38, v39
	v_max3_f32 v153, v153, v40, v41
	v_max3_f32 v153, v153, v42, v43
	v_max3_f32 v153, v153, v44, v45
	v_max3_f32 v153, v153, v46, v47
	v_cmp_lt_f32_e32 vcc, 0x41000000, v153
	s_cbranch_vccz .Lst_norescale_3
	v_mov_b32_e32 v154, v153
	s_nop 1
	v_permlane32_swap_b32_e32 v153, v154
	v_max_f32_e32 v153, v153, v154
	v_max_f32_e32 v154, 0, v153
	v_exp_f32_e64 v152, -v154
	v_sub_f32_e32 v236, v236, v154
	v_sub_f32_e32 v237, v237, v154
	v_sub_f32_e32 v238, v238, v154
	v_sub_f32_e32 v239, v239, v154
	v_sub_f32_e32 v240, v240, v154
	v_sub_f32_e32 v241, v241, v154
	v_sub_f32_e32 v242, v242, v154
	v_sub_f32_e32 v243, v243, v154
	v_sub_f32_e32 v244, v244, v154
	v_sub_f32_e32 v245, v245, v154
	v_sub_f32_e32 v246, v246, v154
	v_sub_f32_e32 v247, v247, v154
	v_sub_f32_e32 v248, v248, v154
	v_sub_f32_e32 v249, v249, v154
	v_sub_f32_e32 v250, v250, v154
	v_sub_f32_e32 v251, v251, v154
	v_pk_mul_f32 v[30:31], v[30:31], v[152:153] op_sel_hi:[1,0]
	v_pk_mul_f32 v[28:29], v[28:29], v[152:153] op_sel_hi:[1,0]
	v_pk_mul_f32 v[26:27], v[26:27], v[152:153] op_sel_hi:[1,0]
	v_pk_mul_f32 v[24:25], v[24:25], v[152:153] op_sel_hi:[1,0]
	v_pk_mul_f32 v[22:23], v[22:23], v[152:153] op_sel_hi:[1,0]
	v_pk_mul_f32 v[20:21], v[20:21], v[152:153] op_sel_hi:[1,0]
	v_pk_mul_f32 v[18:19], v[18:19], v[152:153] op_sel_hi:[1,0]
	v_pk_mul_f32 v[16:17], v[16:17], v[152:153] op_sel_hi:[1,0]
	v_pk_mul_f32 v[14:15], v[14:15], v[152:153] op_sel_hi:[1,0]
	v_pk_mul_f32 v[12:13], v[12:13], v[152:153] op_sel_hi:[1,0]
	v_pk_mul_f32 v[10:11], v[10:11], v[152:153] op_sel_hi:[1,0]
	v_pk_mul_f32 v[8:9], v[8:9], v[152:153] op_sel_hi:[1,0]
	v_pk_mul_f32 v[6:7], v[6:7], v[152:153] op_sel_hi:[1,0]
	v_pk_mul_f32 v[4:5], v[4:5], v[152:153] op_sel_hi:[1,0]
	v_pk_mul_f32 v[2:3], v[2:3], v[152:153] op_sel_hi:[1,0]
	v_pk_mul_f32 v[0:1], v[0:1], v[152:153] op_sel_hi:[1,0]
	v_mul_f32_e32 v151, v151, v152

.Lst_nosm3:
	s_cmp_ge_u32 s93, s51
	s_cbranch_scc1 .Lst_a3_nost
	s_waitcnt vmcnt(0)
	s_and_saveexec_b64 s[66:67], s[8:9]
	ds_write_b128 v203, v[100:103]
	s_mov_b64 exec, s[10:11]
	ds_write_b128 v252, v[104:107]
	s_mov_b64 exec, s[12:13]
	ds_write_b128 v253, v[108:111]
	s_mov_b64 exec, s[66:67]

.Lst_a3_nold:
.Lst_bar2_3:
	s_waitcnt lgkmcnt(0)
	s_barrier
	s_add_i32 s93, s69, 4
	s_cmp_ge_u32 s93, s47
	s_cbranch_scc1 .Lst_exit
	s_cmp_gt_i32 s93, s50
	s_cbranch_scc1 .Lst_nosm4
	ds_read_b128 v[220:223], v194
	ds_read_b128 v[224:227], v194 offset:32
	ds_read_b128 v[228:231], v194 offset:64
	ds_read_b128 v[232:235], v194 offset:96
	ds_read_b128 v[126:129], v194 offset:256
	ds_read_b128 v[130:133], v194 offset:288
	ds_read_b128 v[134:137], v194 offset:10752
	ds_read_b128 v[212:215], v194 offset:10784
	ds_read_b128 v[154:157], v194 offset:10816
	ds_read_b128 v[158:161], v194 offset:10848
	ds_read_b128 v[204:207], v194 offset:11008
	ds_read_b128 v[186:189], v194 offset:11040
	s_waitcnt lgkmcnt(11)
	v_mfma_f32_32x32x16_bf16 v[48:63], v[220:223], v[64:67], v[236:251]
	s_waitcnt lgkmcnt(10)
	v_mfma_f32_32x32x16_bf16 v[48:63], v[224:227], v[68:71], v[48:63]
	s_waitcnt lgkmcnt(9)
	v_mfma_f32_32x32x16_bf16 v[48:63], v[228:231], v[72:75], v[48:63]
	s_waitcnt lgkmcnt(8)
	v_mfma_f32_32x32x16_bf16 v[48:63], v[232:235], v[76:79], v[48:63]
	s_waitcnt lgkmcnt(7)
	v_mfma_f32_32x32x16_bf16 v[48:63], v[126:129], v[80:83], v[48:63]
	s_waitcnt lgkmcnt(6)
	v_mfma_f32_32x32x16_bf16 v[48:63], v[130:133], v[84:87], v[48:63]
	s_waitcnt lgkmcnt(5)
	v_mfma_f32_32x32x16_bf16 v[32:47], v[134:137], v[64:67], v[236:251]
	s_waitcnt lgkmcnt(4)
	v_mfma_f32_32x32x16_bf16 v[32:47], v[212:215], v[68:71], v[32:47]
	s_waitcnt lgkmcnt(3)
	v_mfma_f32_32x32x16_bf16 v[32:47], v[154:157], v[72:75], v[32:47]
	s_waitcnt lgkmcnt(2)
	v_mfma_f32_32x32x16_bf16 v[32:47], v[158:161], v[76:79], v[32:47]
	s_waitcnt lgkmcnt(1)
	v_mfma_f32_32x32x16_bf16 v[32:47], v[204:207], v[80:83], v[32:47]
	s_waitcnt lgkmcnt(0)
	v_mfma_f32_32x32x16_bf16 v[32:47], v[186:189], v[84:87], v[32:47]
	v_max3_f32 v153, v48, v49, v50
	v_max3_f32 v153, v153, v51, v52
	v_max3_f32 v153, v153, v53, v54
	v_max3_f32 v153, v153, v55, v56
	v_max3_f32 v153, v153, v57, v58
	v_max3_f32 v153, v153, v59, v60
	v_max3_f32 v153, v153, v61, v62
	v_max_f32_e32 v153, v153, v63
	s_nop 3
	v_max3_f32 v153, v153, v32, v33
	v_max3_f32 v153, v153, v34, v35
	v_max3_f32 v153, v153, v36, v37
	v_max3_f32 v153, v153, v38, v39
	v_max3_f32 v153, v153, v40, v41
	v_max3_f32 v153, v153, v42, v43
	v_max3_f32 v153, v153, v44, v45
	v_max3_f32 v153, v153, v46, v47
	v_cmp_lt_f32_e32 vcc, 0x41000000, v153
	s_cbranch_vccz .Lst_norescale_4
	v_mov_b32_e32 v154, v153
	s_nop 1
	v_permlane32_swap_b32_e32 v153, v154
	v_max_f32_e32 v153, v153, v154
	v_max_f32_e32 v154, 0, v153
	v_exp_f32_e64 v152, -v154
	v_sub_f32_e32 v236, v236, v154
	v_sub_f32_e32 v237, v237, v154
	v_sub_f32_e32 v238, v238, v154
	v_sub_f32_e32 v239, v239, v154
	v_sub_f32_e32 v240, v240, v154
	v_sub_f32_e32 v241, v241, v154
	v_sub_f32_e32 v242, v242, v154
	v_sub_f32_e32 v243, v243, v154
	v_sub_f32_e32 v244, v244, v154
	v_sub_f32_e32 v245, v245, v154
	v_sub_f32_e32 v246, v246, v154
	v_sub_f32_e32 v247, v247, v154
	v_sub_f32_e32 v248, v248, v154
	v_sub_f32_e32 v249, v249, v154
	v_sub_f32_e32 v250, v250, v154
	v_sub_f32_e32 v251, v251, v154
	v_pk_mul_f32 v[30:31], v[30:31], v[152:153] op_sel_hi:[1,0]
	v_pk_mul_f32 v[28:29], v[28:29], v[152:153] op_sel_hi:[1,0]
	v_pk_mul_f32 v[26:27], v[26:27], v[152:153] op_sel_hi:[1,0]
	v_pk_mul_f32 v[24:25], v[24:25], v[152:153] op_sel_hi:[1,0]
	v_pk_mul_f32 v[22:23], v[22:23], v[152:153] op_sel_hi:[1,0]
	v_pk_mul_f32 v[20:21], v[20:21], v[152:153] op_sel_hi:[1,0]
	v_pk_mul_f32 v[18:19], v[18:19], v[152:153] op_sel_hi:[1,0]
	v_pk_mul_f32 v[16:17], v[16:17], v[152:153] op_sel_hi:[1,0]
	v_pk_mul_f32 v[14:15], v[14:15], v[152:153] op_sel_hi:[1,0]
	v_pk_mul_f32 v[12:13], v[12:13], v[152:153] op_sel_hi:[1,0]
	v_pk_mul_f32 v[10:11], v[10:11], v[152:153] op_sel_hi:[1,0]
	v_pk_mul_f32 v[8:9], v[8:9], v[152:153] op_sel_hi:[1,0]
	v_pk_mul_f32 v[6:7], v[6:7], v[152:153] op_sel_hi:[1,0]
	v_pk_mul_f32 v[4:5], v[4:5], v[152:153] op_sel_hi:[1,0]
	v_pk_mul_f32 v[2:3], v[2:3], v[152:153] op_sel_hi:[1,0]
	v_pk_mul_f32 v[0:1], v[0:1], v[152:153] op_sel_hi:[1,0]
	v_mul_f32_e32 v151, v151, v152

.Lst_nosm4:
	s_cmp_ge_u32 s93, s51
	s_cbranch_scc1 .Lst_a4_nost
	s_waitcnt vmcnt(0)
	s_and_saveexec_b64 s[66:67], s[8:9]
	ds_write_b128 v203, v[112:115] offset:21504
	s_mov_b64 exec, s[10:11]
	ds_write_b128 v252, v[116:119] offset:21504
	s_mov_b64 exec, s[12:13]
	ds_write_b128 v253, v[120:123] offset:21504
	s_mov_b64 exec, s[66:67]

.Lst_a4_nold:
.Lst_bar2_4:
	s_waitcnt lgkmcnt(0)
	s_barrier
	s_add_i32 s93, s69, 5
	s_cmp_ge_u32 s93, s47
	s_cbranch_scc1 .Lst_exit
	s_cmp_gt_i32 s93, s50
	s_cbranch_scc1 .Lst_nosm5
	ds_read_b128 v[220:223], v194 offset:21504
	ds_read_b128 v[224:227], v194 offset:21536
	ds_read_b128 v[228:231], v194 offset:21568
	ds_read_b128 v[232:235], v194 offset:21600
	ds_read_b128 v[126:129], v194 offset:21760
	ds_read_b128 v[130:133], v194 offset:21792
	ds_read_b128 v[134:137], v194 offset:32256
	ds_read_b128 v[212:215], v194 offset:32288
	ds_read_b128 v[154:157], v194 offset:32320
	ds_read_b128 v[158:161], v194 offset:32352
	ds_read_b128 v[204:207], v194 offset:32512
	ds_read_b128 v[186:189], v194 offset:32544
	s_waitcnt lgkmcnt(11)
	v_mfma_f32_32x32x16_bf16 v[48:63], v[220:223], v[64:67], v[236:251]
	s_waitcnt lgkmcnt(10)
	v_mfma_f32_32x32x16_bf16 v[48:63], v[224:227], v[68:71], v[48:63]
	s_waitcnt lgkmcnt(9)
	v_mfma_f32_32x32x16_bf16 v[48:63], v[228:231], v[72:75], v[48:63]
	s_waitcnt lgkmcnt(8)
	v_mfma_f32_32x32x16_bf16 v[48:63], v[232:235], v[76:79], v[48:63]
	s_waitcnt lgkmcnt(7)
	v_mfma_f32_32x32x16_bf16 v[48:63], v[126:129], v[80:83], v[48:63]
	s_waitcnt lgkmcnt(6)
	v_mfma_f32_32x32x16_bf16 v[48:63], v[130:133], v[84:87], v[48:63]
	s_waitcnt lgkmcnt(5)
	v_mfma_f32_32x32x16_bf16 v[32:47], v[134:137], v[64:67], v[236:251]
	s_waitcnt lgkmcnt(4)
	v_mfma_f32_32x32x16_bf16 v[32:47], v[212:215], v[68:71], v[32:47]
	s_waitcnt lgkmcnt(3)
	v_mfma_f32_32x32x16_bf16 v[32:47], v[154:157], v[72:75], v[32:47]
	s_waitcnt lgkmcnt(2)
	v_mfma_f32_32x32x16_bf16 v[32:47], v[158:161], v[76:79], v[32:47]
	s_waitcnt lgkmcnt(1)
	v_mfma_f32_32x32x16_bf16 v[32:47], v[204:207], v[80:83], v[32:47]
	s_waitcnt lgkmcnt(0)
	v_mfma_f32_32x32x16_bf16 v[32:47], v[186:189], v[84:87], v[32:47]
	v_max3_f32 v153, v48, v49, v50
	v_max3_f32 v153, v153, v51, v52
	v_max3_f32 v153, v153, v53, v54
	v_max3_f32 v153, v153, v55, v56
	v_max3_f32 v153, v153, v57, v58
	v_max3_f32 v153, v153, v59, v60
	v_max3_f32 v153, v153, v61, v62
	v_max_f32_e32 v153, v153, v63
	s_nop 3
	v_max3_f32 v153, v153, v32, v33
	v_max3_f32 v153, v153, v34, v35
	v_max3_f32 v153, v153, v36, v37
	v_max3_f32 v153, v153, v38, v39
	v_max3_f32 v153, v153, v40, v41
	v_max3_f32 v153, v153, v42, v43
	v_max3_f32 v153, v153, v44, v45
	v_max3_f32 v153, v153, v46, v47
	v_cmp_lt_f32_e32 vcc, 0x41000000, v153
	s_cbranch_vccz .Lst_norescale_5
	v_mov_b32_e32 v154, v153
	s_nop 1
	v_permlane32_swap_b32_e32 v153, v154
	v_max_f32_e32 v153, v153, v154
	v_max_f32_e32 v154, 0, v153
	v_exp_f32_e64 v152, -v154
	v_sub_f32_e32 v236, v236, v154
	v_sub_f32_e32 v237, v237, v154
	v_sub_f32_e32 v238, v238, v154
	v_sub_f32_e32 v239, v239, v154
	v_sub_f32_e32 v240, v240, v154
	v_sub_f32_e32 v241, v241, v154
	v_sub_f32_e32 v242, v242, v154
	v_sub_f32_e32 v243, v243, v154
	v_sub_f32_e32 v244, v244, v154
	v_sub_f32_e32 v245, v245, v154
	v_sub_f32_e32 v246, v246, v154
	v_sub_f32_e32 v247, v247, v154
	v_sub_f32_e32 v248, v248, v154
	v_sub_f32_e32 v249, v249, v154
	v_sub_f32_e32 v250, v250, v154
	v_sub_f32_e32 v251, v251, v154
	v_pk_mul_f32 v[30:31], v[30:31], v[152:153] op_sel_hi:[1,0]
	v_pk_mul_f32 v[28:29], v[28:29], v[152:153] op_sel_hi:[1,0]
	v_pk_mul_f32 v[26:27], v[26:27], v[152:153] op_sel_hi:[1,0]
	v_pk_mul_f32 v[24:25], v[24:25], v[152:153] op_sel_hi:[1,0]
	v_pk_mul_f32 v[22:23], v[22:23], v[152:153] op_sel_hi:[1,0]
	v_pk_mul_f32 v[20:21], v[20:21], v[152:153] op_sel_hi:[1,0]
	v_pk_mul_f32 v[18:19], v[18:19], v[152:153] op_sel_hi:[1,0]
	v_pk_mul_f32 v[16:17], v[16:17], v[152:153] op_sel_hi:[1,0]
	v_pk_mul_f32 v[14:15], v[14:15], v[152:153] op_sel_hi:[1,0]
	v_pk_mul_f32 v[12:13], v[12:13], v[152:153] op_sel_hi:[1,0]
	v_pk_mul_f32 v[10:11], v[10:11], v[152:153] op_sel_hi:[1,0]
	v_pk_mul_f32 v[8:9], v[8:9], v[152:153] op_sel_hi:[1,0]
	v_pk_mul_f32 v[6:7], v[6:7], v[152:153] op_sel_hi:[1,0]
	v_pk_mul_f32 v[4:5], v[4:5], v[152:153] op_sel_hi:[1,0]
	v_pk_mul_f32 v[2:3], v[2:3], v[152:153] op_sel_hi:[1,0]
	v_pk_mul_f32 v[0:1], v[0:1], v[152:153] op_sel_hi:[1,0]
	v_mul_f32_e32 v151, v151, v152

.Lst_nosm5:
	s_cmp_ge_u32 s93, s51
	s_cbranch_scc1 .Lst_a5_nost
	s_waitcnt vmcnt(0)
	s_and_saveexec_b64 s[66:67], s[8:9]
	ds_write_b128 v203, v[88:91]
	s_mov_b64 exec, s[10:11]
	ds_write_b128 v252, v[92:95]
	s_mov_b64 exec, s[12:13]
	ds_write_b128 v253, v[96:99]
	s_mov_b64 exec, s[66:67]
